# hand-written P0 pooling-fold loop: w_out column loads issued in 4 prefetched passes of 32 (was 8 serialized batches), pool_w/pool_scale broadcast via v_readlane
# speedup vs baseline: 1.0019x; 1.0019x over previous
; __device__ __forceinline__ unsigned pk2(float lo, float hi) { return f2bf(lo) | (f2bf(hi) << 16); }
; __device__ __forceinline__ void phase_prep(const Args& a, LAS unsigned char* lds, int wid, int lane) {
;     ...
;     { bf16_t* WT = (bf16_t*)(ws + WS_WOUT1);
;       for (int it = gw; it < 128 * 16; it += NGW) { const int kq = it >> 4, nb = it & 15, k = 4 * kq, g = k >> 7, i0 = k & 127, n = 64 * nb + lane;
;           float c0 = 0.f, c1 = 0.f, c2 = 0.f, c3 = 0.f;
;           const float* pw = a.pool_w + ((size_t)g * 128 + i0) * 128;
; #pragma unroll 16
;           for (int o = 0; o < 128; ++o) { const float w = a.w_out_1[(size_t)(g * 128 + o) * 1024 + n] * a.pool_scale[g * 128 + o];
;               c0 += pw[o] * w; c1 += pw[128 + o] * w; c2 += pw[256 + o] * w; c3 += pw[384 + o] * w; }
;           u32x2 o2; o2.x = pk2(c0, c1); o2.y = pk2(c2, c3);
;           *(u32x2*)(WT + (size_t)n * 1024 + k) = o2; } }
.LBB0_317:
	v_readlane_b32 s36, v254, 0
	v_readlane_b32 s37, v254, 1
	s_add_u32 s70, s36, 0x2400000
	s_addc_u32 s71, s37, 0
	v_readlane_b32 s38, v254, 2
	v_readlane_b32 s39, v254, 3
	s_cmpk_gt_i32 s3, 0x7ff
	s_mov_b32 s60, s66
	s_cbranch_scc1 .LBB0_322
	v_readlane_b32 s4, v254, 19
	v_readlane_b32 s5, v254, 20
	v_readlane_b32 s10, v254, 9
	v_readlane_b32 s11, v254, 10
	v_readlane_b32 s16, v254, 8
	v_lshlrev_b32_e32 v176, 2, v212
	s_mov_b32 s17, s3
.Lfd_loop:
	s_lshr_b32 s0, s17, 9
	s_lshr_b32 s1, s17, 4
	s_and_b32 s2, s17, 15
	s_lshl_b32 s6, s0, 19
	s_lshl_b32 s7, s2, 8
	s_add_u32 s6, s6, s7
	s_add_u32 s8, s4, s6
	s_addc_u32 s9, s5, 0
	s_lshl_b32 s6, s0, 9
	s_add_u32 s12, s10, s6
	s_addc_u32 s13, s11, 0
	s_and_b32 s6, s1, 31
	s_lshl_b32 s6, s6, 11
	s_lshl_b32 s7, s0, 16
	s_add_u32 s6, s6, s7
	s_add_u32 s14, s18, s6
	s_addc_u32 s15, s19, 0
	global_load_dword v166, v176, s[12:13]
	global_load_dword v167, v176, s[12:13] offset:256
	global_load_dword v168, v176, s[14:15] offset:0
	global_load_dword v169, v176, s[14:15] offset:256
	global_load_dword v170, v176, s[14:15] offset:512
	global_load_dword v171, v176, s[14:15] offset:768
	global_load_dword v172, v176, s[14:15] offset:1024
	global_load_dword v173, v176, s[14:15] offset:1280
	global_load_dword v174, v176, s[14:15] offset:1536
	global_load_dword v175, v176, s[14:15] offset:1792
	v_mov_b32_e32 v177, 0
	v_mov_b32_e32 v178, 0
	v_mov_b32_e32 v179, 0
	v_mov_b32_e32 v180, 0
	global_load_dword v1, v176, s[8:9]
	s_add_u32 s8, s8, 0x1000
	s_addc_u32 s9, s9, 0
	global_load_dword v2, v176, s[8:9]
	s_add_u32 s8, s8, 0x1000
	s_addc_u32 s9, s9, 0
	global_load_dword v3, v176, s[8:9]
	s_add_u32 s8, s8, 0x1000
	s_addc_u32 s9, s9, 0
	global_load_dword v4, v176, s[8:9]
	s_add_u32 s8, s8, 0x1000
	s_addc_u32 s9, s9, 0
	global_load_dword v5, v176, s[8:9]
	s_add_u32 s8, s8, 0x1000
	s_addc_u32 s9, s9, 0
	global_load_dword v6, v176, s[8:9]
	s_add_u32 s8, s8, 0x1000
	s_addc_u32 s9, s9, 0
	global_load_dword v7, v176, s[8:9]
	s_add_u32 s8, s8, 0x1000
	s_addc_u32 s9, s9, 0
	global_load_dword v8, v176, s[8:9]
	s_add_u32 s8, s8, 0x1000
	s_addc_u32 s9, s9, 0
	global_load_dword v9, v176, s[8:9]
	s_add_u32 s8, s8, 0x1000
	s_addc_u32 s9, s9, 0
	global_load_dword v10, v176, s[8:9]
	s_add_u32 s8, s8, 0x1000
	s_addc_u32 s9, s9, 0
	global_load_dword v11, v176, s[8:9]
	s_add_u32 s8, s8, 0x1000
	s_addc_u32 s9, s9, 0
	global_load_dword v12, v176, s[8:9]
	s_add_u32 s8, s8, 0x1000
	s_addc_u32 s9, s9, 0
	global_load_dword v13, v176, s[8:9]
	s_add_u32 s8, s8, 0x1000
	s_addc_u32 s9, s9, 0
	global_load_dword v14, v176, s[8:9]
	s_add_u32 s8, s8, 0x1000
	s_addc_u32 s9, s9, 0
	global_load_dword v15, v176, s[8:9]
	s_add_u32 s8, s8, 0x1000
	s_addc_u32 s9, s9, 0
	global_load_dword v16, v176, s[8:9]
	s_add_u32 s8, s8, 0x1000
	s_addc_u32 s9, s9, 0
	global_load_dword v17, v176, s[8:9]
	s_add_u32 s8, s8, 0x1000
	s_addc_u32 s9, s9, 0
	global_load_dword v18, v176, s[8:9]
	s_add_u32 s8, s8, 0x1000
	s_addc_u32 s9, s9, 0
	global_load_dword v19, v176, s[8:9]
	s_add_u32 s8, s8, 0x1000
	s_addc_u32 s9, s9, 0
	global_load_dword v20, v176, s[8:9]
	s_add_u32 s8, s8, 0x1000
	s_addc_u32 s9, s9, 0
	global_load_dword v21, v176, s[8:9]
	s_add_u32 s8, s8, 0x1000
	s_addc_u32 s9, s9, 0
	global_load_dword v22, v176, s[8:9]
	s_add_u32 s8, s8, 0x1000
	s_addc_u32 s9, s9, 0
	global_load_dword v23, v176, s[8:9]
	s_add_u32 s8, s8, 0x1000
	s_addc_u32 s9, s9, 0
	global_load_dword v24, v176, s[8:9]
	s_add_u32 s8, s8, 0x1000
	s_addc_u32 s9, s9, 0
	global_load_dword v25, v176, s[8:9]
	s_add_u32 s8, s8, 0x1000
	s_addc_u32 s9, s9, 0
	global_load_dword v26, v176, s[8:9]
	s_add_u32 s8, s8, 0x1000
	s_addc_u32 s9, s9, 0
	global_load_dword v27, v176, s[8:9]
	s_add_u32 s8, s8, 0x1000
	s_addc_u32 s9, s9, 0
	global_load_dword v28, v176, s[8:9]
	s_add_u32 s8, s8, 0x1000
	s_addc_u32 s9, s9, 0
	global_load_dword v29, v176, s[8:9]
	s_add_u32 s8, s8, 0x1000
	s_addc_u32 s9, s9, 0
	global_load_dword v30, v176, s[8:9]
	s_add_u32 s8, s8, 0x1000
	s_addc_u32 s9, s9, 0
	global_load_dword v31, v176, s[8:9]
	s_add_u32 s8, s8, 0x1000
	s_addc_u32 s9, s9, 0
	global_load_dword v32, v176, s[8:9]
	s_add_u32 s8, s8, 0x1000
	s_addc_u32 s9, s9, 0
	s_waitcnt vmcnt(0)
	global_load_dword v33, v176, s[8:9]
	s_add_u32 s8, s8, 0x1000
	s_addc_u32 s9, s9, 0
	global_load_dword v34, v176, s[8:9]
	s_add_u32 s8, s8, 0x1000
	s_addc_u32 s9, s9, 0
	global_load_dword v35, v176, s[8:9]
	s_add_u32 s8, s8, 0x1000
	s_addc_u32 s9, s9, 0
	global_load_dword v36, v176, s[8:9]
	s_add_u32 s8, s8, 0x1000
	s_addc_u32 s9, s9, 0
	global_load_dword v37, v176, s[8:9]
	s_add_u32 s8, s8, 0x1000
	s_addc_u32 s9, s9, 0
	global_load_dword v38, v176, s[8:9]
	s_add_u32 s8, s8, 0x1000
	s_addc_u32 s9, s9, 0
	global_load_dword v39, v176, s[8:9]
	s_add_u32 s8, s8, 0x1000
	s_addc_u32 s9, s9, 0
	global_load_dword v40, v176, s[8:9]
	s_add_u32 s8, s8, 0x1000
	s_addc_u32 s9, s9, 0
	global_load_dword v41, v176, s[8:9]
	s_add_u32 s8, s8, 0x1000
	s_addc_u32 s9, s9, 0
	global_load_dword v42, v176, s[8:9]
	s_add_u32 s8, s8, 0x1000
	s_addc_u32 s9, s9, 0
	global_load_dword v43, v176, s[8:9]
	s_add_u32 s8, s8, 0x1000
	s_addc_u32 s9, s9, 0
	global_load_dword v44, v176, s[8:9]
	s_add_u32 s8, s8, 0x1000
	s_addc_u32 s9, s9, 0
	global_load_dword v45, v176, s[8:9]
	s_add_u32 s8, s8, 0x1000
	s_addc_u32 s9, s9, 0
	global_load_dword v46, v176, s[8:9]
	s_add_u32 s8, s8, 0x1000
	s_addc_u32 s9, s9, 0
	global_load_dword v47, v176, s[8:9]
	s_add_u32 s8, s8, 0x1000
	s_addc_u32 s9, s9, 0
	global_load_dword v48, v176, s[8:9]
	s_add_u32 s8, s8, 0x1000
	s_addc_u32 s9, s9, 0
	global_load_dword v49, v176, s[8:9]
	s_add_u32 s8, s8, 0x1000
	s_addc_u32 s9, s9, 0
	global_load_dword v50, v176, s[8:9]
; __device__ __forceinline__ void phase_prep(const Args& a, LAS unsigned char* lds, int wid, int lane) {
;     ...
;           const float* pw = a.pool_w + ((size_t)g * 128 + i0) * 128;
; #pragma unroll 16
;           for (int o = 0; o < 128; ++o) { const float w = a.w_out_1[(size_t)(g * 128 + o) * 1024 + n] * a.pool_scale[g * 128 + o];
;               c0 += pw[o] * w; c1 += pw[128 + o] * w; c2 += pw[256 + o] * w; c3 += pw[384 + o] * w; }
	s_add_u32 s8, s8, 0x1000
	s_addc_u32 s9, s9, 0
	global_load_dword v51, v176, s[8:9]
	s_add_u32 s8, s8, 0x1000
	s_addc_u32 s9, s9, 0
	global_load_dword v52, v176, s[8:9]
	s_add_u32 s8, s8, 0x1000
	s_addc_u32 s9, s9, 0
	global_load_dword v53, v176, s[8:9]
	s_add_u32 s8, s8, 0x1000
	s_addc_u32 s9, s9, 0
	global_load_dword v54, v176, s[8:9]
	s_add_u32 s8, s8, 0x1000
	s_addc_u32 s9, s9, 0
	global_load_dword v55, v176, s[8:9]
	s_add_u32 s8, s8, 0x1000
	s_addc_u32 s9, s9, 0
	global_load_dword v56, v176, s[8:9]
	s_add_u32 s8, s8, 0x1000
	s_addc_u32 s9, s9, 0
	global_load_dword v57, v176, s[8:9]
	s_add_u32 s8, s8, 0x1000
	s_addc_u32 s9, s9, 0
	global_load_dword v58, v176, s[8:9]
	s_add_u32 s8, s8, 0x1000
	s_addc_u32 s9, s9, 0
	global_load_dword v59, v176, s[8:9]
	s_add_u32 s8, s8, 0x1000
	s_addc_u32 s9, s9, 0
	global_load_dword v60, v176, s[8:9]
	s_add_u32 s8, s8, 0x1000
	s_addc_u32 s9, s9, 0
	global_load_dword v61, v176, s[8:9]
	s_add_u32 s8, s8, 0x1000
	s_addc_u32 s9, s9, 0
	global_load_dword v62, v176, s[8:9]
	s_add_u32 s8, s8, 0x1000
	s_addc_u32 s9, s9, 0
	global_load_dword v63, v176, s[8:9]
	s_add_u32 s8, s8, 0x1000
	s_addc_u32 s9, s9, 0
	global_load_dword v64, v176, s[8:9]
	s_add_u32 s8, s8, 0x1000
	s_addc_u32 s9, s9, 0
	v_readlane_b32 s22, v166, 0
	v_readlane_b32 s23, v168, 0
	v_readlane_b32 s27, v170, 0
	v_readlane_b32 s28, v172, 0
	v_readlane_b32 s29, v174, 0
	v_mul_f32_e32 v1, s22, v1
	v_fmac_f32_e32 v177, s23, v1
	v_fmac_f32_e32 v178, s27, v1
	v_fmac_f32_e32 v179, s28, v1
	v_fmac_f32_e32 v180, s29, v1
	v_readlane_b32 s22, v166, 1
	v_readlane_b32 s23, v168, 1
	v_readlane_b32 s27, v170, 1
	v_readlane_b32 s28, v172, 1
	v_readlane_b32 s29, v174, 1
	v_mul_f32_e32 v2, s22, v2
	v_fmac_f32_e32 v177, s23, v2
	v_fmac_f32_e32 v178, s27, v2
	v_fmac_f32_e32 v179, s28, v2
	v_fmac_f32_e32 v180, s29, v2
	v_readlane_b32 s22, v166, 2
	v_readlane_b32 s23, v168, 2
	v_readlane_b32 s27, v170, 2
	v_readlane_b32 s28, v172, 2
	v_readlane_b32 s29, v174, 2
	v_mul_f32_e32 v3, s22, v3
	v_fmac_f32_e32 v177, s23, v3
	v_fmac_f32_e32 v178, s27, v3
	v_fmac_f32_e32 v179, s28, v3
	v_fmac_f32_e32 v180, s29, v3
	v_readlane_b32 s22, v166, 3
	v_readlane_b32 s23, v168, 3
	v_readlane_b32 s27, v170, 3
	v_readlane_b32 s28, v172, 3
	v_readlane_b32 s29, v174, 3
	v_mul_f32_e32 v4, s22, v4
	v_fmac_f32_e32 v177, s23, v4
	v_fmac_f32_e32 v178, s27, v4
	v_fmac_f32_e32 v179, s28, v4
	v_fmac_f32_e32 v180, s29, v4
	v_readlane_b32 s22, v166, 4
	v_readlane_b32 s23, v168, 4
	v_readlane_b32 s27, v170, 4
	v_readlane_b32 s28, v172, 4
	v_readlane_b32 s29, v174, 4
	v_mul_f32_e32 v5, s22, v5
	v_fmac_f32_e32 v177, s23, v5
	v_fmac_f32_e32 v178, s27, v5
	v_fmac_f32_e32 v179, s28, v5
	v_fmac_f32_e32 v180, s29, v5
	v_readlane_b32 s22, v166, 5
	v_readlane_b32 s23, v168, 5
	v_readlane_b32 s27, v170, 5
	v_readlane_b32 s28, v172, 5
	v_readlane_b32 s29, v174, 5
	v_mul_f32_e32 v6, s22, v6
	v_fmac_f32_e32 v177, s23, v6
	v_fmac_f32_e32 v178, s27, v6
	v_fmac_f32_e32 v179, s28, v6
	v_fmac_f32_e32 v180, s29, v6
	v_readlane_b32 s22, v166, 6
	v_readlane_b32 s23, v168, 6
	v_readlane_b32 s27, v170, 6
	v_readlane_b32 s28, v172, 6
	v_readlane_b32 s29, v174, 6
	v_mul_f32_e32 v7, s22, v7
	v_fmac_f32_e32 v177, s23, v7
	v_fmac_f32_e32 v178, s27, v7
	v_fmac_f32_e32 v179, s28, v7
	v_fmac_f32_e32 v180, s29, v7
	v_readlane_b32 s22, v166, 7
	v_readlane_b32 s23, v168, 7
	v_readlane_b32 s27, v170, 7
	v_readlane_b32 s28, v172, 7
	v_readlane_b32 s29, v174, 7
	v_mul_f32_e32 v8, s22, v8
	v_fmac_f32_e32 v177, s23, v8
	v_fmac_f32_e32 v178, s27, v8
	v_fmac_f32_e32 v179, s28, v8
	v_fmac_f32_e32 v180, s29, v8
	v_readlane_b32 s22, v166, 8
	v_readlane_b32 s23, v168, 8
	v_readlane_b32 s27, v170, 8
	v_readlane_b32 s28, v172, 8
	v_readlane_b32 s29, v174, 8
	v_mul_f32_e32 v9, s22, v9
	v_fmac_f32_e32 v177, s23, v9
	v_fmac_f32_e32 v178, s27, v9
	v_fmac_f32_e32 v179, s28, v9
	v_fmac_f32_e32 v180, s29, v9
	v_readlane_b32 s22, v166, 9
	v_readlane_b32 s23, v168, 9
	v_readlane_b32 s27, v170, 9
	v_readlane_b32 s28, v172, 9
	v_readlane_b32 s29, v174, 9
	v_mul_f32_e32 v10, s22, v10
	v_fmac_f32_e32 v177, s23, v10
	v_fmac_f32_e32 v178, s27, v10
	v_fmac_f32_e32 v179, s28, v10
	v_fmac_f32_e32 v180, s29, v10
	v_readlane_b32 s22, v166, 10
	v_readlane_b32 s23, v168, 10
	v_readlane_b32 s27, v170, 10
	v_readlane_b32 s28, v172, 10
	v_readlane_b32 s29, v174, 10
	v_mul_f32_e32 v11, s22, v11
	v_fmac_f32_e32 v177, s23, v11
	v_fmac_f32_e32 v178, s27, v11
	v_fmac_f32_e32 v179, s28, v11
	v_fmac_f32_e32 v180, s29, v11
	v_readlane_b32 s22, v166, 11
	v_readlane_b32 s23, v168, 11
	v_readlane_b32 s27, v170, 11
	v_readlane_b32 s28, v172, 11
	v_readlane_b32 s29, v174, 11
	v_mul_f32_e32 v12, s22, v12
	v_fmac_f32_e32 v177, s23, v12
	v_fmac_f32_e32 v178, s27, v12
	v_fmac_f32_e32 v179, s28, v12
	v_fmac_f32_e32 v180, s29, v12
	v_readlane_b32 s22, v166, 12
	v_readlane_b32 s23, v168, 12
	v_readlane_b32 s27, v170, 12
	v_readlane_b32 s28, v172, 12
	v_readlane_b32 s29, v174, 12
	v_mul_f32_e32 v13, s22, v13
	v_fmac_f32_e32 v177, s23, v13
	v_fmac_f32_e32 v178, s27, v13
	v_fmac_f32_e32 v179, s28, v13
	v_fmac_f32_e32 v180, s29, v13
	v_readlane_b32 s22, v166, 13
	v_readlane_b32 s23, v168, 13
	v_readlane_b32 s27, v170, 13
	v_readlane_b32 s28, v172, 13
	v_readlane_b32 s29, v174, 13
	v_mul_f32_e32 v14, s22, v14
	v_fmac_f32_e32 v177, s23, v14
	v_fmac_f32_e32 v178, s27, v14
	v_fmac_f32_e32 v179, s28, v14
	v_fmac_f32_e32 v180, s29, v14
	v_readlane_b32 s22, v166, 14
	v_readlane_b32 s23, v168, 14
	v_readlane_b32 s27, v170, 14
	v_readlane_b32 s28, v172, 14
	v_readlane_b32 s29, v174, 14
	v_mul_f32_e32 v15, s22, v15
	v_fmac_f32_e32 v177, s23, v15
	v_fmac_f32_e32 v178, s27, v15
	v_fmac_f32_e32 v179, s28, v15
; __device__ __forceinline__ void phase_prep(const Args& a, LAS unsigned char* lds, int wid, int lane) {
;     ...
;           const float* pw = a.pool_w + ((size_t)g * 128 + i0) * 128;
; #pragma unroll 16
;           for (int o = 0; o < 128; ++o) { const float w = a.w_out_1[(size_t)(g * 128 + o) * 1024 + n] * a.pool_scale[g * 128 + o];
;               c0 += pw[o] * w; c1 += pw[128 + o] * w; c2 += pw[256 + o] * w; c3 += pw[384 + o] * w; }
	v_fmac_f32_e32 v180, s29, v15
	v_readlane_b32 s22, v166, 15
	v_readlane_b32 s23, v168, 15
	v_readlane_b32 s27, v170, 15
	v_readlane_b32 s28, v172, 15
	v_readlane_b32 s29, v174, 15
	v_mul_f32_e32 v16, s22, v16
	v_fmac_f32_e32 v177, s23, v16
	v_fmac_f32_e32 v178, s27, v16
	v_fmac_f32_e32 v179, s28, v16
	v_fmac_f32_e32 v180, s29, v16
	v_readlane_b32 s22, v166, 16
	v_readlane_b32 s23, v168, 16
	v_readlane_b32 s27, v170, 16
	v_readlane_b32 s28, v172, 16
	v_readlane_b32 s29, v174, 16
	v_mul_f32_e32 v17, s22, v17
	v_fmac_f32_e32 v177, s23, v17
	v_fmac_f32_e32 v178, s27, v17
	v_fmac_f32_e32 v179, s28, v17
	v_fmac_f32_e32 v180, s29, v17
	v_readlane_b32 s22, v166, 17
	v_readlane_b32 s23, v168, 17
	v_readlane_b32 s27, v170, 17
	v_readlane_b32 s28, v172, 17
	v_readlane_b32 s29, v174, 17
	v_mul_f32_e32 v18, s22, v18
	v_fmac_f32_e32 v177, s23, v18
	v_fmac_f32_e32 v178, s27, v18
	v_fmac_f32_e32 v179, s28, v18
	v_fmac_f32_e32 v180, s29, v18
	v_readlane_b32 s22, v166, 18
	v_readlane_b32 s23, v168, 18
	v_readlane_b32 s27, v170, 18
	v_readlane_b32 s28, v172, 18
	v_readlane_b32 s29, v174, 18
	v_mul_f32_e32 v19, s22, v19
	v_fmac_f32_e32 v177, s23, v19
	v_fmac_f32_e32 v178, s27, v19
	v_fmac_f32_e32 v179, s28, v19
	v_fmac_f32_e32 v180, s29, v19
	v_readlane_b32 s22, v166, 19
	v_readlane_b32 s23, v168, 19
	v_readlane_b32 s27, v170, 19
	v_readlane_b32 s28, v172, 19
	v_readlane_b32 s29, v174, 19
	v_mul_f32_e32 v20, s22, v20
	v_fmac_f32_e32 v177, s23, v20
	v_fmac_f32_e32 v178, s27, v20
	v_fmac_f32_e32 v179, s28, v20
	v_fmac_f32_e32 v180, s29, v20
	v_readlane_b32 s22, v166, 20
	v_readlane_b32 s23, v168, 20
	v_readlane_b32 s27, v170, 20
	v_readlane_b32 s28, v172, 20
	v_readlane_b32 s29, v174, 20
	v_mul_f32_e32 v21, s22, v21
	v_fmac_f32_e32 v177, s23, v21
	v_fmac_f32_e32 v178, s27, v21
	v_fmac_f32_e32 v179, s28, v21
	v_fmac_f32_e32 v180, s29, v21
	v_readlane_b32 s22, v166, 21
	v_readlane_b32 s23, v168, 21
	v_readlane_b32 s27, v170, 21
	v_readlane_b32 s28, v172, 21
	v_readlane_b32 s29, v174, 21
	v_mul_f32_e32 v22, s22, v22
	v_fmac_f32_e32 v177, s23, v22
	v_fmac_f32_e32 v178, s27, v22
	v_fmac_f32_e32 v179, s28, v22
	v_fmac_f32_e32 v180, s29, v22
	v_readlane_b32 s22, v166, 22
	v_readlane_b32 s23, v168, 22
	v_readlane_b32 s27, v170, 22
	v_readlane_b32 s28, v172, 22
	v_readlane_b32 s29, v174, 22
	v_mul_f32_e32 v23, s22, v23
	v_fmac_f32_e32 v177, s23, v23
	v_fmac_f32_e32 v178, s27, v23
	v_fmac_f32_e32 v179, s28, v23
	v_fmac_f32_e32 v180, s29, v23
	v_readlane_b32 s22, v166, 23
	v_readlane_b32 s23, v168, 23
	v_readlane_b32 s27, v170, 23
	v_readlane_b32 s28, v172, 23
	v_readlane_b32 s29, v174, 23
	v_mul_f32_e32 v24, s22, v24
	v_fmac_f32_e32 v177, s23, v24
	v_fmac_f32_e32 v178, s27, v24
	v_fmac_f32_e32 v179, s28, v24
	v_fmac_f32_e32 v180, s29, v24
	v_readlane_b32 s22, v166, 24
	v_readlane_b32 s23, v168, 24
	v_readlane_b32 s27, v170, 24
	v_readlane_b32 s28, v172, 24
	v_readlane_b32 s29, v174, 24
	v_mul_f32_e32 v25, s22, v25
	v_fmac_f32_e32 v177, s23, v25
	v_fmac_f32_e32 v178, s27, v25
	v_fmac_f32_e32 v179, s28, v25
	v_fmac_f32_e32 v180, s29, v25
	v_readlane_b32 s22, v166, 25
	v_readlane_b32 s23, v168, 25
	v_readlane_b32 s27, v170, 25
	v_readlane_b32 s28, v172, 25
	v_readlane_b32 s29, v174, 25
	v_mul_f32_e32 v26, s22, v26
	v_fmac_f32_e32 v177, s23, v26
	v_fmac_f32_e32 v178, s27, v26
	v_fmac_f32_e32 v179, s28, v26
	v_fmac_f32_e32 v180, s29, v26
	v_readlane_b32 s22, v166, 26
	v_readlane_b32 s23, v168, 26
	v_readlane_b32 s27, v170, 26
	v_readlane_b32 s28, v172, 26
	v_readlane_b32 s29, v174, 26
	v_mul_f32_e32 v27, s22, v27
	v_fmac_f32_e32 v177, s23, v27
	v_fmac_f32_e32 v178, s27, v27
	v_fmac_f32_e32 v179, s28, v27
	v_fmac_f32_e32 v180, s29, v27
	v_readlane_b32 s22, v166, 27
	v_readlane_b32 s23, v168, 27
	v_readlane_b32 s27, v170, 27
	v_readlane_b32 s28, v172, 27
	v_readlane_b32 s29, v174, 27
	v_mul_f32_e32 v28, s22, v28
	v_fmac_f32_e32 v177, s23, v28
	v_fmac_f32_e32 v178, s27, v28
	v_fmac_f32_e32 v179, s28, v28
	v_fmac_f32_e32 v180, s29, v28
	v_readlane_b32 s22, v166, 28
	v_readlane_b32 s23, v168, 28
	v_readlane_b32 s27, v170, 28
	v_readlane_b32 s28, v172, 28
	v_readlane_b32 s29, v174, 28
	v_mul_f32_e32 v29, s22, v29
	v_fmac_f32_e32 v177, s23, v29
	v_fmac_f32_e32 v178, s27, v29
	v_fmac_f32_e32 v179, s28, v29
	v_fmac_f32_e32 v180, s29, v29
	v_readlane_b32 s22, v166, 29
	v_readlane_b32 s23, v168, 29
	v_readlane_b32 s27, v170, 29
	v_readlane_b32 s28, v172, 29
	v_readlane_b32 s29, v174, 29
	v_mul_f32_e32 v30, s22, v30
	v_fmac_f32_e32 v177, s23, v30
	v_fmac_f32_e32 v178, s27, v30
	v_fmac_f32_e32 v179, s28, v30
	v_fmac_f32_e32 v180, s29, v30
	v_readlane_b32 s22, v166, 30
	v_readlane_b32 s23, v168, 30
	v_readlane_b32 s27, v170, 30
	v_readlane_b32 s28, v172, 30
	v_readlane_b32 s29, v174, 30
	v_mul_f32_e32 v31, s22, v31
	v_fmac_f32_e32 v177, s23, v31
	v_fmac_f32_e32 v178, s27, v31
	v_fmac_f32_e32 v179, s28, v31
	v_fmac_f32_e32 v180, s29, v31
	v_readlane_b32 s22, v166, 31
	v_readlane_b32 s23, v168, 31
	v_readlane_b32 s27, v170, 31
	v_readlane_b32 s28, v172, 31
	v_readlane_b32 s29, v174, 31
	v_mul_f32_e32 v32, s22, v32
	v_fmac_f32_e32 v177, s23, v32
	v_fmac_f32_e32 v178, s27, v32
	v_fmac_f32_e32 v179, s28, v32
	v_fmac_f32_e32 v180, s29, v32
	s_waitcnt vmcnt(0)
; __device__ __forceinline__ void phase_prep(const Args& a, LAS unsigned char* lds, int wid, int lane) {
;     ...
;           const float* pw = a.pool_w + ((size_t)g * 128 + i0) * 128;
; #pragma unroll 16
;           for (int o = 0; o < 128; ++o) { const float w = a.w_out_1[(size_t)(g * 128 + o) * 1024 + n] * a.pool_scale[g * 128 + o];
;               c0 += pw[o] * w; c1 += pw[128 + o] * w; c2 += pw[256 + o] * w; c3 += pw[384 + o] * w; }
	global_load_dword v1, v176, s[8:9]
	s_add_u32 s8, s8, 0x1000
	s_addc_u32 s9, s9, 0
	global_load_dword v2, v176, s[8:9]
	s_add_u32 s8, s8, 0x1000
	s_addc_u32 s9, s9, 0
	global_load_dword v3, v176, s[8:9]
	s_add_u32 s8, s8, 0x1000
	s_addc_u32 s9, s9, 0
	global_load_dword v4, v176, s[8:9]
	s_add_u32 s8, s8, 0x1000
	s_addc_u32 s9, s9, 0
	global_load_dword v5, v176, s[8:9]
	s_add_u32 s8, s8, 0x1000
	s_addc_u32 s9, s9, 0
	global_load_dword v6, v176, s[8:9]
	s_add_u32 s8, s8, 0x1000
	s_addc_u32 s9, s9, 0
	global_load_dword v7, v176, s[8:9]
	s_add_u32 s8, s8, 0x1000
	s_addc_u32 s9, s9, 0
	global_load_dword v8, v176, s[8:9]
	s_add_u32 s8, s8, 0x1000
	s_addc_u32 s9, s9, 0
	global_load_dword v9, v176, s[8:9]
	s_add_u32 s8, s8, 0x1000
	s_addc_u32 s9, s9, 0
	global_load_dword v10, v176, s[8:9]
	s_add_u32 s8, s8, 0x1000
	s_addc_u32 s9, s9, 0
	global_load_dword v11, v176, s[8:9]
	s_add_u32 s8, s8, 0x1000
	s_addc_u32 s9, s9, 0
	global_load_dword v12, v176, s[8:9]
	s_add_u32 s8, s8, 0x1000
	s_addc_u32 s9, s9, 0
	global_load_dword v13, v176, s[8:9]
	s_add_u32 s8, s8, 0x1000
	s_addc_u32 s9, s9, 0
	global_load_dword v14, v176, s[8:9]
	s_add_u32 s8, s8, 0x1000
	s_addc_u32 s9, s9, 0
	global_load_dword v15, v176, s[8:9]
	s_add_u32 s8, s8, 0x1000
	s_addc_u32 s9, s9, 0
	global_load_dword v16, v176, s[8:9]
	s_add_u32 s8, s8, 0x1000
	s_addc_u32 s9, s9, 0
	global_load_dword v17, v176, s[8:9]
	s_add_u32 s8, s8, 0x1000
	s_addc_u32 s9, s9, 0
	global_load_dword v18, v176, s[8:9]
	s_add_u32 s8, s8, 0x1000
	s_addc_u32 s9, s9, 0
	global_load_dword v19, v176, s[8:9]
	s_add_u32 s8, s8, 0x1000
	s_addc_u32 s9, s9, 0
	global_load_dword v20, v176, s[8:9]
	s_add_u32 s8, s8, 0x1000
	s_addc_u32 s9, s9, 0
	global_load_dword v21, v176, s[8:9]
	s_add_u32 s8, s8, 0x1000
	s_addc_u32 s9, s9, 0
	global_load_dword v22, v176, s[8:9]
	s_add_u32 s8, s8, 0x1000
	s_addc_u32 s9, s9, 0
	global_load_dword v23, v176, s[8:9]
	s_add_u32 s8, s8, 0x1000
	s_addc_u32 s9, s9, 0
	global_load_dword v24, v176, s[8:9]
	s_add_u32 s8, s8, 0x1000
	s_addc_u32 s9, s9, 0
	global_load_dword v25, v176, s[8:9]
	s_add_u32 s8, s8, 0x1000
	s_addc_u32 s9, s9, 0
	global_load_dword v26, v176, s[8:9]
	s_add_u32 s8, s8, 0x1000
	s_addc_u32 s9, s9, 0
	global_load_dword v27, v176, s[8:9]
	s_add_u32 s8, s8, 0x1000
	s_addc_u32 s9, s9, 0
	global_load_dword v28, v176, s[8:9]
	s_add_u32 s8, s8, 0x1000
	s_addc_u32 s9, s9, 0
	global_load_dword v29, v176, s[8:9]
	s_add_u32 s8, s8, 0x1000
	s_addc_u32 s9, s9, 0
	global_load_dword v30, v176, s[8:9]
	s_add_u32 s8, s8, 0x1000
	s_addc_u32 s9, s9, 0
	global_load_dword v31, v176, s[8:9]
	s_add_u32 s8, s8, 0x1000
	s_addc_u32 s9, s9, 0
	global_load_dword v32, v176, s[8:9]
	s_add_u32 s8, s8, 0x1000
	s_addc_u32 s9, s9, 0
	v_readlane_b32 s22, v166, 32
	v_readlane_b32 s23, v168, 32
	v_readlane_b32 s27, v170, 32
	v_readlane_b32 s28, v172, 32
	v_readlane_b32 s29, v174, 32
	v_mul_f32_e32 v33, s22, v33
	v_fmac_f32_e32 v177, s23, v33
	v_fmac_f32_e32 v178, s27, v33
	v_fmac_f32_e32 v179, s28, v33
	v_fmac_f32_e32 v180, s29, v33
	v_readlane_b32 s22, v166, 33
	v_readlane_b32 s23, v168, 33
	v_readlane_b32 s27, v170, 33
	v_readlane_b32 s28, v172, 33
	v_readlane_b32 s29, v174, 33
	v_mul_f32_e32 v34, s22, v34
	v_fmac_f32_e32 v177, s23, v34
	v_fmac_f32_e32 v178, s27, v34
	v_fmac_f32_e32 v179, s28, v34
	v_fmac_f32_e32 v180, s29, v34
	v_readlane_b32 s22, v166, 34
	v_readlane_b32 s23, v168, 34
	v_readlane_b32 s27, v170, 34
	v_readlane_b32 s28, v172, 34
	v_readlane_b32 s29, v174, 34
	v_mul_f32_e32 v35, s22, v35
	v_fmac_f32_e32 v177, s23, v35
	v_fmac_f32_e32 v178, s27, v35
	v_fmac_f32_e32 v179, s28, v35
	v_fmac_f32_e32 v180, s29, v35
	v_readlane_b32 s22, v166, 35
	v_readlane_b32 s23, v168, 35
	v_readlane_b32 s27, v170, 35
	v_readlane_b32 s28, v172, 35
	v_readlane_b32 s29, v174, 35
	v_mul_f32_e32 v36, s22, v36
	v_fmac_f32_e32 v177, s23, v36
	v_fmac_f32_e32 v178, s27, v36
	v_fmac_f32_e32 v179, s28, v36
	v_fmac_f32_e32 v180, s29, v36
	v_readlane_b32 s22, v166, 36
	v_readlane_b32 s23, v168, 36
	v_readlane_b32 s27, v170, 36
	v_readlane_b32 s28, v172, 36
	v_readlane_b32 s29, v174, 36
	v_mul_f32_e32 v37, s22, v37
	v_fmac_f32_e32 v177, s23, v37
	v_fmac_f32_e32 v178, s27, v37
	v_fmac_f32_e32 v179, s28, v37
	v_fmac_f32_e32 v180, s29, v37
	v_readlane_b32 s22, v166, 37
	v_readlane_b32 s23, v168, 37
	v_readlane_b32 s27, v170, 37
	v_readlane_b32 s28, v172, 37
	v_readlane_b32 s29, v174, 37
	v_mul_f32_e32 v38, s22, v38
	v_fmac_f32_e32 v177, s23, v38
	v_fmac_f32_e32 v178, s27, v38
	v_fmac_f32_e32 v179, s28, v38
	v_fmac_f32_e32 v180, s29, v38
	v_readlane_b32 s22, v166, 38
	v_readlane_b32 s23, v168, 38
	v_readlane_b32 s27, v170, 38
	v_readlane_b32 s28, v172, 38
	v_readlane_b32 s29, v174, 38
	v_mul_f32_e32 v39, s22, v39
	v_fmac_f32_e32 v177, s23, v39
	v_fmac_f32_e32 v178, s27, v39
	v_fmac_f32_e32 v179, s28, v39
	v_fmac_f32_e32 v180, s29, v39
	v_readlane_b32 s22, v166, 39
	v_readlane_b32 s23, v168, 39
	v_readlane_b32 s27, v170, 39
	v_readlane_b32 s28, v172, 39
	v_readlane_b32 s29, v174, 39
	v_mul_f32_e32 v40, s22, v40
	v_fmac_f32_e32 v177, s23, v40
	v_fmac_f32_e32 v178, s27, v40
	v_fmac_f32_e32 v179, s28, v40
	v_fmac_f32_e32 v180, s29, v40
	v_readlane_b32 s22, v166, 40
	v_readlane_b32 s23, v168, 40
	v_readlane_b32 s27, v170, 40
	v_readlane_b32 s28, v172, 40
	v_readlane_b32 s29, v174, 40
	v_mul_f32_e32 v41, s22, v41
	v_fmac_f32_e32 v177, s23, v41
	v_fmac_f32_e32 v178, s27, v41
	v_fmac_f32_e32 v179, s28, v41
	v_fmac_f32_e32 v180, s29, v41
	v_readlane_b32 s22, v166, 41
	v_readlane_b32 s23, v168, 41
	v_readlane_b32 s27, v170, 41
	v_readlane_b32 s28, v172, 41
	v_readlane_b32 s29, v174, 41
	v_mul_f32_e32 v42, s22, v42
	v_fmac_f32_e32 v177, s23, v42
; __device__ __forceinline__ void phase_prep(const Args& a, LAS unsigned char* lds, int wid, int lane) {
;     ...
;           const float* pw = a.pool_w + ((size_t)g * 128 + i0) * 128;
; #pragma unroll 16
;           for (int o = 0; o < 128; ++o) { const float w = a.w_out_1[(size_t)(g * 128 + o) * 1024 + n] * a.pool_scale[g * 128 + o];
;               c0 += pw[o] * w; c1 += pw[128 + o] * w; c2 += pw[256 + o] * w; c3 += pw[384 + o] * w; }
	v_fmac_f32_e32 v178, s27, v42
	v_fmac_f32_e32 v179, s28, v42
	v_fmac_f32_e32 v180, s29, v42
	v_readlane_b32 s22, v166, 42
	v_readlane_b32 s23, v168, 42
	v_readlane_b32 s27, v170, 42
	v_readlane_b32 s28, v172, 42
	v_readlane_b32 s29, v174, 42
	v_mul_f32_e32 v43, s22, v43
	v_fmac_f32_e32 v177, s23, v43
	v_fmac_f32_e32 v178, s27, v43
	v_fmac_f32_e32 v179, s28, v43
	v_fmac_f32_e32 v180, s29, v43
	v_readlane_b32 s22, v166, 43
	v_readlane_b32 s23, v168, 43
	v_readlane_b32 s27, v170, 43
	v_readlane_b32 s28, v172, 43
	v_readlane_b32 s29, v174, 43
	v_mul_f32_e32 v44, s22, v44
	v_fmac_f32_e32 v177, s23, v44
	v_fmac_f32_e32 v178, s27, v44
	v_fmac_f32_e32 v179, s28, v44
	v_fmac_f32_e32 v180, s29, v44
	v_readlane_b32 s22, v166, 44
	v_readlane_b32 s23, v168, 44
	v_readlane_b32 s27, v170, 44
	v_readlane_b32 s28, v172, 44
	v_readlane_b32 s29, v174, 44
	v_mul_f32_e32 v45, s22, v45
	v_fmac_f32_e32 v177, s23, v45
	v_fmac_f32_e32 v178, s27, v45
	v_fmac_f32_e32 v179, s28, v45
	v_fmac_f32_e32 v180, s29, v45
	v_readlane_b32 s22, v166, 45
	v_readlane_b32 s23, v168, 45
	v_readlane_b32 s27, v170, 45
	v_readlane_b32 s28, v172, 45
	v_readlane_b32 s29, v174, 45
	v_mul_f32_e32 v46, s22, v46
	v_fmac_f32_e32 v177, s23, v46
	v_fmac_f32_e32 v178, s27, v46
	v_fmac_f32_e32 v179, s28, v46
	v_fmac_f32_e32 v180, s29, v46
	v_readlane_b32 s22, v166, 46
	v_readlane_b32 s23, v168, 46
	v_readlane_b32 s27, v170, 46
	v_readlane_b32 s28, v172, 46
	v_readlane_b32 s29, v174, 46
	v_mul_f32_e32 v47, s22, v47
	v_fmac_f32_e32 v177, s23, v47
	v_fmac_f32_e32 v178, s27, v47
	v_fmac_f32_e32 v179, s28, v47
	v_fmac_f32_e32 v180, s29, v47
	v_readlane_b32 s22, v166, 47
	v_readlane_b32 s23, v168, 47
	v_readlane_b32 s27, v170, 47
	v_readlane_b32 s28, v172, 47
	v_readlane_b32 s29, v174, 47
	v_mul_f32_e32 v48, s22, v48
	v_fmac_f32_e32 v177, s23, v48
	v_fmac_f32_e32 v178, s27, v48
	v_fmac_f32_e32 v179, s28, v48
	v_fmac_f32_e32 v180, s29, v48
	v_readlane_b32 s22, v166, 48
	v_readlane_b32 s23, v168, 48
	v_readlane_b32 s27, v170, 48
	v_readlane_b32 s28, v172, 48
	v_readlane_b32 s29, v174, 48
	v_mul_f32_e32 v49, s22, v49
	v_fmac_f32_e32 v177, s23, v49
	v_fmac_f32_e32 v178, s27, v49
	v_fmac_f32_e32 v179, s28, v49
	v_fmac_f32_e32 v180, s29, v49
	v_readlane_b32 s22, v166, 49
	v_readlane_b32 s23, v168, 49
	v_readlane_b32 s27, v170, 49
	v_readlane_b32 s28, v172, 49
	v_readlane_b32 s29, v174, 49
	v_mul_f32_e32 v50, s22, v50
	v_fmac_f32_e32 v177, s23, v50
	v_fmac_f32_e32 v178, s27, v50
	v_fmac_f32_e32 v179, s28, v50
	v_fmac_f32_e32 v180, s29, v50
	v_readlane_b32 s22, v166, 50
	v_readlane_b32 s23, v168, 50
	v_readlane_b32 s27, v170, 50
	v_readlane_b32 s28, v172, 50
	v_readlane_b32 s29, v174, 50
	v_mul_f32_e32 v51, s22, v51
	v_fmac_f32_e32 v177, s23, v51
	v_fmac_f32_e32 v178, s27, v51
	v_fmac_f32_e32 v179, s28, v51
	v_fmac_f32_e32 v180, s29, v51
	v_readlane_b32 s22, v166, 51
	v_readlane_b32 s23, v168, 51
	v_readlane_b32 s27, v170, 51
	v_readlane_b32 s28, v172, 51
	v_readlane_b32 s29, v174, 51
	v_mul_f32_e32 v52, s22, v52
	v_fmac_f32_e32 v177, s23, v52
	v_fmac_f32_e32 v178, s27, v52
	v_fmac_f32_e32 v179, s28, v52
	v_fmac_f32_e32 v180, s29, v52
	v_readlane_b32 s22, v166, 52
	v_readlane_b32 s23, v168, 52
	v_readlane_b32 s27, v170, 52
	v_readlane_b32 s28, v172, 52
	v_readlane_b32 s29, v174, 52
	v_mul_f32_e32 v53, s22, v53
	v_fmac_f32_e32 v177, s23, v53
	v_fmac_f32_e32 v178, s27, v53
	v_fmac_f32_e32 v179, s28, v53
	v_fmac_f32_e32 v180, s29, v53
	v_readlane_b32 s22, v166, 53
	v_readlane_b32 s23, v168, 53
	v_readlane_b32 s27, v170, 53
	v_readlane_b32 s28, v172, 53
	v_readlane_b32 s29, v174, 53
	v_mul_f32_e32 v54, s22, v54
	v_fmac_f32_e32 v177, s23, v54
	v_fmac_f32_e32 v178, s27, v54
	v_fmac_f32_e32 v179, s28, v54
	v_fmac_f32_e32 v180, s29, v54
	v_readlane_b32 s22, v166, 54
	v_readlane_b32 s23, v168, 54
	v_readlane_b32 s27, v170, 54
	v_readlane_b32 s28, v172, 54
	v_readlane_b32 s29, v174, 54
	v_mul_f32_e32 v55, s22, v55
	v_fmac_f32_e32 v177, s23, v55
	v_fmac_f32_e32 v178, s27, v55
	v_fmac_f32_e32 v179, s28, v55
	v_fmac_f32_e32 v180, s29, v55
	v_readlane_b32 s22, v166, 55
	v_readlane_b32 s23, v168, 55
	v_readlane_b32 s27, v170, 55
	v_readlane_b32 s28, v172, 55
	v_readlane_b32 s29, v174, 55
	v_mul_f32_e32 v56, s22, v56
	v_fmac_f32_e32 v177, s23, v56
	v_fmac_f32_e32 v178, s27, v56
	v_fmac_f32_e32 v179, s28, v56
	v_fmac_f32_e32 v180, s29, v56
	v_readlane_b32 s22, v166, 56
	v_readlane_b32 s23, v168, 56
	v_readlane_b32 s27, v170, 56
	v_readlane_b32 s28, v172, 56
	v_readlane_b32 s29, v174, 56
	v_mul_f32_e32 v57, s22, v57
	v_fmac_f32_e32 v177, s23, v57
	v_fmac_f32_e32 v178, s27, v57
	v_fmac_f32_e32 v179, s28, v57
	v_fmac_f32_e32 v180, s29, v57
	v_readlane_b32 s22, v166, 57
	v_readlane_b32 s23, v168, 57
	v_readlane_b32 s27, v170, 57
	v_readlane_b32 s28, v172, 57
	v_readlane_b32 s29, v174, 57
	v_mul_f32_e32 v58, s22, v58
	v_fmac_f32_e32 v177, s23, v58
	v_fmac_f32_e32 v178, s27, v58
	v_fmac_f32_e32 v179, s28, v58
	v_fmac_f32_e32 v180, s29, v58
	v_readlane_b32 s22, v166, 58
	v_readlane_b32 s23, v168, 58
	v_readlane_b32 s27, v170, 58
	v_readlane_b32 s28, v172, 58
	v_readlane_b32 s29, v174, 58
	v_mul_f32_e32 v59, s22, v59
	v_fmac_f32_e32 v177, s23, v59
	v_fmac_f32_e32 v178, s27, v59
	v_fmac_f32_e32 v179, s28, v59
	v_fmac_f32_e32 v180, s29, v59
	v_readlane_b32 s22, v166, 59
	v_readlane_b32 s23, v168, 59
	v_readlane_b32 s27, v170, 59
	v_readlane_b32 s28, v172, 59
	v_readlane_b32 s29, v174, 59
	v_mul_f32_e32 v60, s22, v60
	v_fmac_f32_e32 v177, s23, v60
	v_fmac_f32_e32 v178, s27, v60
	v_fmac_f32_e32 v179, s28, v60
	v_fmac_f32_e32 v180, s29, v60
	v_readlane_b32 s22, v166, 60
	v_readlane_b32 s23, v168, 60
	v_readlane_b32 s27, v170, 60
	v_readlane_b32 s28, v172, 60
	v_readlane_b32 s29, v174, 60
	v_mul_f32_e32 v61, s22, v61
	v_fmac_f32_e32 v177, s23, v61
	v_fmac_f32_e32 v178, s27, v61
	v_fmac_f32_e32 v179, s28, v61
	v_fmac_f32_e32 v180, s29, v61
	v_readlane_b32 s22, v166, 61
	v_readlane_b32 s23, v168, 61
	v_readlane_b32 s27, v170, 61
	v_readlane_b32 s28, v172, 61
	v_readlane_b32 s29, v174, 61
	v_mul_f32_e32 v62, s22, v62
	v_fmac_f32_e32 v177, s23, v62
	v_fmac_f32_e32 v178, s27, v62
	v_fmac_f32_e32 v179, s28, v62
	v_fmac_f32_e32 v180, s29, v62
	v_readlane_b32 s22, v166, 62
	v_readlane_b32 s23, v168, 62
	v_readlane_b32 s27, v170, 62
	v_readlane_b32 s28, v172, 62
	v_readlane_b32 s29, v174, 62
	v_mul_f32_e32 v63, s22, v63
	v_fmac_f32_e32 v177, s23, v63
	v_fmac_f32_e32 v178, s27, v63
	v_fmac_f32_e32 v179, s28, v63
	v_fmac_f32_e32 v180, s29, v63
	v_readlane_b32 s22, v166, 63
	v_readlane_b32 s23, v168, 63
	v_readlane_b32 s27, v170, 63
	v_readlane_b32 s28, v172, 63
	v_readlane_b32 s29, v174, 63
	v_mul_f32_e32 v64, s22, v64
	v_fmac_f32_e32 v177, s23, v64
	v_fmac_f32_e32 v178, s27, v64
	v_fmac_f32_e32 v179, s28, v64
	v_fmac_f32_e32 v180, s29, v64
	s_waitcnt vmcnt(0)
; __device__ __forceinline__ void phase_prep(const Args& a, LAS unsigned char* lds, int wid, int lane) {
;     ...
;           const float* pw = a.pool_w + ((size_t)g * 128 + i0) * 128;
; #pragma unroll 16
;           for (int o = 0; o < 128; ++o) { const float w = a.w_out_1[(size_t)(g * 128 + o) * 1024 + n] * a.pool_scale[g * 128 + o];
;               c0 += pw[o] * w; c1 += pw[128 + o] * w; c2 += pw[256 + o] * w; c3 += pw[384 + o] * w; }
	global_load_dword v33, v176, s[8:9]
	s_add_u32 s8, s8, 0x1000
	s_addc_u32 s9, s9, 0
	global_load_dword v34, v176, s[8:9]
	s_add_u32 s8, s8, 0x1000
	s_addc_u32 s9, s9, 0
	global_load_dword v35, v176, s[8:9]
	s_add_u32 s8, s8, 0x1000
	s_addc_u32 s9, s9, 0
	global_load_dword v36, v176, s[8:9]
	s_add_u32 s8, s8, 0x1000
	s_addc_u32 s9, s9, 0
	global_load_dword v37, v176, s[8:9]
	s_add_u32 s8, s8, 0x1000
	s_addc_u32 s9, s9, 0
	global_load_dword v38, v176, s[8:9]
	s_add_u32 s8, s8, 0x1000
	s_addc_u32 s9, s9, 0
	global_load_dword v39, v176, s[8:9]
	s_add_u32 s8, s8, 0x1000
	s_addc_u32 s9, s9, 0
	global_load_dword v40, v176, s[8:9]
	s_add_u32 s8, s8, 0x1000
	s_addc_u32 s9, s9, 0
	global_load_dword v41, v176, s[8:9]
	s_add_u32 s8, s8, 0x1000
	s_addc_u32 s9, s9, 0
	global_load_dword v42, v176, s[8:9]
	s_add_u32 s8, s8, 0x1000
	s_addc_u32 s9, s9, 0
	global_load_dword v43, v176, s[8:9]
	s_add_u32 s8, s8, 0x1000
	s_addc_u32 s9, s9, 0
	global_load_dword v44, v176, s[8:9]
	s_add_u32 s8, s8, 0x1000
	s_addc_u32 s9, s9, 0
	global_load_dword v45, v176, s[8:9]
	s_add_u32 s8, s8, 0x1000
	s_addc_u32 s9, s9, 0
	global_load_dword v46, v176, s[8:9]
	s_add_u32 s8, s8, 0x1000
	s_addc_u32 s9, s9, 0
	global_load_dword v47, v176, s[8:9]
	s_add_u32 s8, s8, 0x1000
	s_addc_u32 s9, s9, 0
	global_load_dword v48, v176, s[8:9]
	s_add_u32 s8, s8, 0x1000
	s_addc_u32 s9, s9, 0
	global_load_dword v49, v176, s[8:9]
	s_add_u32 s8, s8, 0x1000
	s_addc_u32 s9, s9, 0
	global_load_dword v50, v176, s[8:9]
	s_add_u32 s8, s8, 0x1000
	s_addc_u32 s9, s9, 0
	global_load_dword v51, v176, s[8:9]
	s_add_u32 s8, s8, 0x1000
	s_addc_u32 s9, s9, 0
	global_load_dword v52, v176, s[8:9]
	s_add_u32 s8, s8, 0x1000
	s_addc_u32 s9, s9, 0
	global_load_dword v53, v176, s[8:9]
	s_add_u32 s8, s8, 0x1000
	s_addc_u32 s9, s9, 0
	global_load_dword v54, v176, s[8:9]
	s_add_u32 s8, s8, 0x1000
	s_addc_u32 s9, s9, 0
	global_load_dword v55, v176, s[8:9]
	s_add_u32 s8, s8, 0x1000
	s_addc_u32 s9, s9, 0
	global_load_dword v56, v176, s[8:9]
	s_add_u32 s8, s8, 0x1000
	s_addc_u32 s9, s9, 0
	global_load_dword v57, v176, s[8:9]
	s_add_u32 s8, s8, 0x1000
	s_addc_u32 s9, s9, 0
	global_load_dword v58, v176, s[8:9]
	s_add_u32 s8, s8, 0x1000
	s_addc_u32 s9, s9, 0
	global_load_dword v59, v176, s[8:9]
	s_add_u32 s8, s8, 0x1000
	s_addc_u32 s9, s9, 0
	global_load_dword v60, v176, s[8:9]
	s_add_u32 s8, s8, 0x1000
	s_addc_u32 s9, s9, 0
	global_load_dword v61, v176, s[8:9]
	s_add_u32 s8, s8, 0x1000
	s_addc_u32 s9, s9, 0
	global_load_dword v62, v176, s[8:9]
	s_add_u32 s8, s8, 0x1000
	s_addc_u32 s9, s9, 0
	global_load_dword v63, v176, s[8:9]
	s_add_u32 s8, s8, 0x1000
	s_addc_u32 s9, s9, 0
	global_load_dword v64, v176, s[8:9]
	s_add_u32 s8, s8, 0x1000
	s_addc_u32 s9, s9, 0
	v_readlane_b32 s22, v167, 0
	v_readlane_b32 s23, v169, 0
	v_readlane_b32 s27, v171, 0
	v_readlane_b32 s28, v173, 0
	v_readlane_b32 s29, v175, 0
	v_mul_f32_e32 v1, s22, v1
	v_fmac_f32_e32 v177, s23, v1
	v_fmac_f32_e32 v178, s27, v1
	v_fmac_f32_e32 v179, s28, v1
	v_fmac_f32_e32 v180, s29, v1
	v_readlane_b32 s22, v167, 1
	v_readlane_b32 s23, v169, 1
	v_readlane_b32 s27, v171, 1
	v_readlane_b32 s28, v173, 1
	v_readlane_b32 s29, v175, 1
	v_mul_f32_e32 v2, s22, v2
	v_fmac_f32_e32 v177, s23, v2
	v_fmac_f32_e32 v178, s27, v2
	v_fmac_f32_e32 v179, s28, v2
	v_fmac_f32_e32 v180, s29, v2
	v_readlane_b32 s22, v167, 2
	v_readlane_b32 s23, v169, 2
	v_readlane_b32 s27, v171, 2
	v_readlane_b32 s28, v173, 2
	v_readlane_b32 s29, v175, 2
	v_mul_f32_e32 v3, s22, v3
	v_fmac_f32_e32 v177, s23, v3
	v_fmac_f32_e32 v178, s27, v3
	v_fmac_f32_e32 v179, s28, v3
	v_fmac_f32_e32 v180, s29, v3
	v_readlane_b32 s22, v167, 3
	v_readlane_b32 s23, v169, 3
	v_readlane_b32 s27, v171, 3
	v_readlane_b32 s28, v173, 3
	v_readlane_b32 s29, v175, 3
	v_mul_f32_e32 v4, s22, v4
	v_fmac_f32_e32 v177, s23, v4
	v_fmac_f32_e32 v178, s27, v4
	v_fmac_f32_e32 v179, s28, v4
	v_fmac_f32_e32 v180, s29, v4
	v_readlane_b32 s22, v167, 4
	v_readlane_b32 s23, v169, 4
	v_readlane_b32 s27, v171, 4
	v_readlane_b32 s28, v173, 4
	v_readlane_b32 s29, v175, 4
	v_mul_f32_e32 v5, s22, v5
	v_fmac_f32_e32 v177, s23, v5
	v_fmac_f32_e32 v178, s27, v5
	v_fmac_f32_e32 v179, s28, v5
	v_fmac_f32_e32 v180, s29, v5
	v_readlane_b32 s22, v167, 5
	v_readlane_b32 s23, v169, 5
	v_readlane_b32 s27, v171, 5
	v_readlane_b32 s28, v173, 5
	v_readlane_b32 s29, v175, 5
	v_mul_f32_e32 v6, s22, v6
	v_fmac_f32_e32 v177, s23, v6
	v_fmac_f32_e32 v178, s27, v6
	v_fmac_f32_e32 v179, s28, v6
	v_fmac_f32_e32 v180, s29, v6
	v_readlane_b32 s22, v167, 6
	v_readlane_b32 s23, v169, 6
	v_readlane_b32 s27, v171, 6
	v_readlane_b32 s28, v173, 6
	v_readlane_b32 s29, v175, 6
	v_mul_f32_e32 v7, s22, v7
	v_fmac_f32_e32 v177, s23, v7
	v_fmac_f32_e32 v178, s27, v7
	v_fmac_f32_e32 v179, s28, v7
	v_fmac_f32_e32 v180, s29, v7
	v_readlane_b32 s22, v167, 7
	v_readlane_b32 s23, v169, 7
	v_readlane_b32 s27, v171, 7
	v_readlane_b32 s28, v173, 7
	v_readlane_b32 s29, v175, 7
	v_mul_f32_e32 v8, s22, v8
	v_fmac_f32_e32 v177, s23, v8
	v_fmac_f32_e32 v178, s27, v8
	v_fmac_f32_e32 v179, s28, v8
	v_fmac_f32_e32 v180, s29, v8
	v_readlane_b32 s22, v167, 8
	v_readlane_b32 s23, v169, 8
	v_readlane_b32 s27, v171, 8
	v_readlane_b32 s28, v173, 8
	v_readlane_b32 s29, v175, 8
	v_mul_f32_e32 v9, s22, v9
	v_fmac_f32_e32 v177, s23, v9
	v_fmac_f32_e32 v178, s27, v9
	v_fmac_f32_e32 v179, s28, v9
	v_fmac_f32_e32 v180, s29, v9
	v_readlane_b32 s22, v167, 9
	v_readlane_b32 s23, v169, 9
	v_readlane_b32 s27, v171, 9
	v_readlane_b32 s28, v173, 9
	v_readlane_b32 s29, v175, 9
	v_mul_f32_e32 v10, s22, v10
	v_fmac_f32_e32 v177, s23, v10
	v_fmac_f32_e32 v178, s27, v10
	v_fmac_f32_e32 v179, s28, v10
	v_fmac_f32_e32 v180, s29, v10
; __device__ __forceinline__ void phase_prep(const Args& a, LAS unsigned char* lds, int wid, int lane) {
;     ...
;           const float* pw = a.pool_w + ((size_t)g * 128 + i0) * 128;
; #pragma unroll 16
;           for (int o = 0; o < 128; ++o) { const float w = a.w_out_1[(size_t)(g * 128 + o) * 1024 + n] * a.pool_scale[g * 128 + o];
;               c0 += pw[o] * w; c1 += pw[128 + o] * w; c2 += pw[256 + o] * w; c3 += pw[384 + o] * w; }
	v_readlane_b32 s22, v167, 10
	v_readlane_b32 s23, v169, 10
	v_readlane_b32 s27, v171, 10
	v_readlane_b32 s28, v173, 10
	v_readlane_b32 s29, v175, 10
	v_mul_f32_e32 v11, s22, v11
	v_fmac_f32_e32 v177, s23, v11
	v_fmac_f32_e32 v178, s27, v11
	v_fmac_f32_e32 v179, s28, v11
	v_fmac_f32_e32 v180, s29, v11
	v_readlane_b32 s22, v167, 11
	v_readlane_b32 s23, v169, 11
	v_readlane_b32 s27, v171, 11
	v_readlane_b32 s28, v173, 11
	v_readlane_b32 s29, v175, 11
	v_mul_f32_e32 v12, s22, v12
	v_fmac_f32_e32 v177, s23, v12
	v_fmac_f32_e32 v178, s27, v12
	v_fmac_f32_e32 v179, s28, v12
	v_fmac_f32_e32 v180, s29, v12
	v_readlane_b32 s22, v167, 12
	v_readlane_b32 s23, v169, 12
	v_readlane_b32 s27, v171, 12
	v_readlane_b32 s28, v173, 12
	v_readlane_b32 s29, v175, 12
	v_mul_f32_e32 v13, s22, v13
	v_fmac_f32_e32 v177, s23, v13
	v_fmac_f32_e32 v178, s27, v13
	v_fmac_f32_e32 v179, s28, v13
	v_fmac_f32_e32 v180, s29, v13
	v_readlane_b32 s22, v167, 13
	v_readlane_b32 s23, v169, 13
	v_readlane_b32 s27, v171, 13
	v_readlane_b32 s28, v173, 13
	v_readlane_b32 s29, v175, 13
	v_mul_f32_e32 v14, s22, v14
	v_fmac_f32_e32 v177, s23, v14
	v_fmac_f32_e32 v178, s27, v14
	v_fmac_f32_e32 v179, s28, v14
	v_fmac_f32_e32 v180, s29, v14
	v_readlane_b32 s22, v167, 14
	v_readlane_b32 s23, v169, 14
	v_readlane_b32 s27, v171, 14
	v_readlane_b32 s28, v173, 14
	v_readlane_b32 s29, v175, 14
	v_mul_f32_e32 v15, s22, v15
	v_fmac_f32_e32 v177, s23, v15
	v_fmac_f32_e32 v178, s27, v15
	v_fmac_f32_e32 v179, s28, v15
	v_fmac_f32_e32 v180, s29, v15
	v_readlane_b32 s22, v167, 15
	v_readlane_b32 s23, v169, 15
	v_readlane_b32 s27, v171, 15
	v_readlane_b32 s28, v173, 15
	v_readlane_b32 s29, v175, 15
	v_mul_f32_e32 v16, s22, v16
	v_fmac_f32_e32 v177, s23, v16
	v_fmac_f32_e32 v178, s27, v16
	v_fmac_f32_e32 v179, s28, v16
	v_fmac_f32_e32 v180, s29, v16
	v_readlane_b32 s22, v167, 16
	v_readlane_b32 s23, v169, 16
	v_readlane_b32 s27, v171, 16
	v_readlane_b32 s28, v173, 16
	v_readlane_b32 s29, v175, 16
	v_mul_f32_e32 v17, s22, v17
	v_fmac_f32_e32 v177, s23, v17
	v_fmac_f32_e32 v178, s27, v17
	v_fmac_f32_e32 v179, s28, v17
	v_fmac_f32_e32 v180, s29, v17
	v_readlane_b32 s22, v167, 17
	v_readlane_b32 s23, v169, 17
	v_readlane_b32 s27, v171, 17
	v_readlane_b32 s28, v173, 17
	v_readlane_b32 s29, v175, 17
	v_mul_f32_e32 v18, s22, v18
	v_fmac_f32_e32 v177, s23, v18
	v_fmac_f32_e32 v178, s27, v18
	v_fmac_f32_e32 v179, s28, v18
	v_fmac_f32_e32 v180, s29, v18
	v_readlane_b32 s22, v167, 18
	v_readlane_b32 s23, v169, 18
	v_readlane_b32 s27, v171, 18
	v_readlane_b32 s28, v173, 18
	v_readlane_b32 s29, v175, 18
	v_mul_f32_e32 v19, s22, v19
	v_fmac_f32_e32 v177, s23, v19
	v_fmac_f32_e32 v178, s27, v19
	v_fmac_f32_e32 v179, s28, v19
	v_fmac_f32_e32 v180, s29, v19
	v_readlane_b32 s22, v167, 19
	v_readlane_b32 s23, v169, 19
	v_readlane_b32 s27, v171, 19
	v_readlane_b32 s28, v173, 19
	v_readlane_b32 s29, v175, 19
	v_mul_f32_e32 v20, s22, v20
	v_fmac_f32_e32 v177, s23, v20
	v_fmac_f32_e32 v178, s27, v20
	v_fmac_f32_e32 v179, s28, v20
	v_fmac_f32_e32 v180, s29, v20
	v_readlane_b32 s22, v167, 20
	v_readlane_b32 s23, v169, 20
	v_readlane_b32 s27, v171, 20
	v_readlane_b32 s28, v173, 20
	v_readlane_b32 s29, v175, 20
	v_mul_f32_e32 v21, s22, v21
	v_fmac_f32_e32 v177, s23, v21
	v_fmac_f32_e32 v178, s27, v21
	v_fmac_f32_e32 v179, s28, v21
	v_fmac_f32_e32 v180, s29, v21
	v_readlane_b32 s22, v167, 21
	v_readlane_b32 s23, v169, 21
	v_readlane_b32 s27, v171, 21
	v_readlane_b32 s28, v173, 21
	v_readlane_b32 s29, v175, 21
	v_mul_f32_e32 v22, s22, v22
	v_fmac_f32_e32 v177, s23, v22
	v_fmac_f32_e32 v178, s27, v22
	v_fmac_f32_e32 v179, s28, v22
	v_fmac_f32_e32 v180, s29, v22
	v_readlane_b32 s22, v167, 22
	v_readlane_b32 s23, v169, 22
	v_readlane_b32 s27, v171, 22
	v_readlane_b32 s28, v173, 22
	v_readlane_b32 s29, v175, 22
	v_mul_f32_e32 v23, s22, v23
	v_fmac_f32_e32 v177, s23, v23
	v_fmac_f32_e32 v178, s27, v23
	v_fmac_f32_e32 v179, s28, v23
	v_fmac_f32_e32 v180, s29, v23
	v_readlane_b32 s22, v167, 23
	v_readlane_b32 s23, v169, 23
	v_readlane_b32 s27, v171, 23
	v_readlane_b32 s28, v173, 23
	v_readlane_b32 s29, v175, 23
	v_mul_f32_e32 v24, s22, v24
	v_fmac_f32_e32 v177, s23, v24
	v_fmac_f32_e32 v178, s27, v24
	v_fmac_f32_e32 v179, s28, v24
	v_fmac_f32_e32 v180, s29, v24
	v_readlane_b32 s22, v167, 24
	v_readlane_b32 s23, v169, 24
	v_readlane_b32 s27, v171, 24
	v_readlane_b32 s28, v173, 24
	v_readlane_b32 s29, v175, 24
	v_mul_f32_e32 v25, s22, v25
	v_fmac_f32_e32 v177, s23, v25
	v_fmac_f32_e32 v178, s27, v25
	v_fmac_f32_e32 v179, s28, v25
	v_fmac_f32_e32 v180, s29, v25
	v_readlane_b32 s22, v167, 25
	v_readlane_b32 s23, v169, 25
	v_readlane_b32 s27, v171, 25
	v_readlane_b32 s28, v173, 25
	v_readlane_b32 s29, v175, 25
	v_mul_f32_e32 v26, s22, v26
	v_fmac_f32_e32 v177, s23, v26
	v_fmac_f32_e32 v178, s27, v26
	v_fmac_f32_e32 v179, s28, v26
	v_fmac_f32_e32 v180, s29, v26
	v_readlane_b32 s22, v167, 26
	v_readlane_b32 s23, v169, 26
	v_readlane_b32 s27, v171, 26
	v_readlane_b32 s28, v173, 26
	v_readlane_b32 s29, v175, 26
	v_mul_f32_e32 v27, s22, v27
	v_fmac_f32_e32 v177, s23, v27
	v_fmac_f32_e32 v178, s27, v27
	v_fmac_f32_e32 v179, s28, v27
	v_fmac_f32_e32 v180, s29, v27
	v_readlane_b32 s22, v167, 27
	v_readlane_b32 s23, v169, 27
	v_readlane_b32 s27, v171, 27
	v_readlane_b32 s28, v173, 27
	v_readlane_b32 s29, v175, 27
	v_mul_f32_e32 v28, s22, v28
	v_fmac_f32_e32 v177, s23, v28
	v_fmac_f32_e32 v178, s27, v28
	v_fmac_f32_e32 v179, s28, v28
	v_fmac_f32_e32 v180, s29, v28
	v_readlane_b32 s22, v167, 28
	v_readlane_b32 s23, v169, 28
	v_readlane_b32 s27, v171, 28
	v_readlane_b32 s28, v173, 28
	v_readlane_b32 s29, v175, 28
	v_mul_f32_e32 v29, s22, v29
	v_fmac_f32_e32 v177, s23, v29
	v_fmac_f32_e32 v178, s27, v29
	v_fmac_f32_e32 v179, s28, v29
	v_fmac_f32_e32 v180, s29, v29
	v_readlane_b32 s22, v167, 29
	v_readlane_b32 s23, v169, 29
	v_readlane_b32 s27, v171, 29
	v_readlane_b32 s28, v173, 29
	v_readlane_b32 s29, v175, 29
	v_mul_f32_e32 v30, s22, v30
	v_fmac_f32_e32 v177, s23, v30
	v_fmac_f32_e32 v178, s27, v30
	v_fmac_f32_e32 v179, s28, v30
	v_fmac_f32_e32 v180, s29, v30
	v_readlane_b32 s22, v167, 30
	v_readlane_b32 s23, v169, 30
	v_readlane_b32 s27, v171, 30
	v_readlane_b32 s28, v173, 30
	v_readlane_b32 s29, v175, 30
	v_mul_f32_e32 v31, s22, v31
	v_fmac_f32_e32 v177, s23, v31
	v_fmac_f32_e32 v178, s27, v31
	v_fmac_f32_e32 v179, s28, v31
	v_fmac_f32_e32 v180, s29, v31
	v_readlane_b32 s22, v167, 31
	v_readlane_b32 s23, v169, 31
	v_readlane_b32 s27, v171, 31
	v_readlane_b32 s28, v173, 31
	v_readlane_b32 s29, v175, 31
	v_mul_f32_e32 v32, s22, v32
	v_fmac_f32_e32 v177, s23, v32
	v_fmac_f32_e32 v178, s27, v32
	v_fmac_f32_e32 v179, s28, v32
	v_fmac_f32_e32 v180, s29, v32
	s_waitcnt vmcnt(0)
; __device__ __forceinline__ void phase_prep(const Args& a, LAS unsigned char* lds, int wid, int lane) {
;     ...
;           for (int o = 0; o < 128; ++o) { const float w = a.w_out_1[(size_t)(g * 128 + o) * 1024 + n] * a.pool_scale[g * 128 + o];
;               c0 += pw[o] * w; c1 += pw[128 + o] * w; c2 += pw[256 + o] * w; c3 += pw[384 + o] * w; }
	v_readlane_b32 s22, v167, 32
	v_readlane_b32 s23, v169, 32
	v_readlane_b32 s27, v171, 32
	v_readlane_b32 s28, v173, 32
	v_readlane_b32 s29, v175, 32
	v_mul_f32_e32 v33, s22, v33
	v_fmac_f32_e32 v177, s23, v33
	v_fmac_f32_e32 v178, s27, v33
	v_fmac_f32_e32 v179, s28, v33
	v_fmac_f32_e32 v180, s29, v33
	v_readlane_b32 s22, v167, 33
	v_readlane_b32 s23, v169, 33
	v_readlane_b32 s27, v171, 33
	v_readlane_b32 s28, v173, 33
	v_readlane_b32 s29, v175, 33
	v_mul_f32_e32 v34, s22, v34
	v_fmac_f32_e32 v177, s23, v34
	v_fmac_f32_e32 v178, s27, v34
	v_fmac_f32_e32 v179, s28, v34
	v_fmac_f32_e32 v180, s29, v34
	v_readlane_b32 s22, v167, 34
	v_readlane_b32 s23, v169, 34
	v_readlane_b32 s27, v171, 34
	v_readlane_b32 s28, v173, 34
	v_readlane_b32 s29, v175, 34
	v_mul_f32_e32 v35, s22, v35
	v_fmac_f32_e32 v177, s23, v35
	v_fmac_f32_e32 v178, s27, v35
	v_fmac_f32_e32 v179, s28, v35
	v_fmac_f32_e32 v180, s29, v35
	v_readlane_b32 s22, v167, 35
	v_readlane_b32 s23, v169, 35
	v_readlane_b32 s27, v171, 35
	v_readlane_b32 s28, v173, 35
	v_readlane_b32 s29, v175, 35
	v_mul_f32_e32 v36, s22, v36
	v_fmac_f32_e32 v177, s23, v36
	v_fmac_f32_e32 v178, s27, v36
	v_fmac_f32_e32 v179, s28, v36
	v_fmac_f32_e32 v180, s29, v36
	v_readlane_b32 s22, v167, 36
	v_readlane_b32 s23, v169, 36
	v_readlane_b32 s27, v171, 36
	v_readlane_b32 s28, v173, 36
	v_readlane_b32 s29, v175, 36
	v_mul_f32_e32 v37, s22, v37
	v_fmac_f32_e32 v177, s23, v37
	v_fmac_f32_e32 v178, s27, v37
	v_fmac_f32_e32 v179, s28, v37
	v_fmac_f32_e32 v180, s29, v37
	v_readlane_b32 s22, v167, 37
	v_readlane_b32 s23, v169, 37
	v_readlane_b32 s27, v171, 37
	v_readlane_b32 s28, v173, 37
	v_readlane_b32 s29, v175, 37
	v_mul_f32_e32 v38, s22, v38
	v_fmac_f32_e32 v177, s23, v38
	v_fmac_f32_e32 v178, s27, v38
	v_fmac_f32_e32 v179, s28, v38
	v_fmac_f32_e32 v180, s29, v38
	v_readlane_b32 s22, v167, 38
	v_readlane_b32 s23, v169, 38
	v_readlane_b32 s27, v171, 38
	v_readlane_b32 s28, v173, 38
	v_readlane_b32 s29, v175, 38
	v_mul_f32_e32 v39, s22, v39
	v_fmac_f32_e32 v177, s23, v39
	v_fmac_f32_e32 v178, s27, v39
	v_fmac_f32_e32 v179, s28, v39
	v_fmac_f32_e32 v180, s29, v39
	v_readlane_b32 s22, v167, 39
	v_readlane_b32 s23, v169, 39
	v_readlane_b32 s27, v171, 39
	v_readlane_b32 s28, v173, 39
	v_readlane_b32 s29, v175, 39
	v_mul_f32_e32 v40, s22, v40
	v_fmac_f32_e32 v177, s23, v40
	v_fmac_f32_e32 v178, s27, v40
	v_fmac_f32_e32 v179, s28, v40
	v_fmac_f32_e32 v180, s29, v40
	v_readlane_b32 s22, v167, 40
	v_readlane_b32 s23, v169, 40
	v_readlane_b32 s27, v171, 40
	v_readlane_b32 s28, v173, 40
	v_readlane_b32 s29, v175, 40
	v_mul_f32_e32 v41, s22, v41
	v_fmac_f32_e32 v177, s23, v41
	v_fmac_f32_e32 v178, s27, v41
	v_fmac_f32_e32 v179, s28, v41
	v_fmac_f32_e32 v180, s29, v41
	v_readlane_b32 s22, v167, 41
	v_readlane_b32 s23, v169, 41
	v_readlane_b32 s27, v171, 41
	v_readlane_b32 s28, v173, 41
	v_readlane_b32 s29, v175, 41
	v_mul_f32_e32 v42, s22, v42
	v_fmac_f32_e32 v177, s23, v42
	v_fmac_f32_e32 v178, s27, v42
	v_fmac_f32_e32 v179, s28, v42
	v_fmac_f32_e32 v180, s29, v42
	v_readlane_b32 s22, v167, 42
	v_readlane_b32 s23, v169, 42
	v_readlane_b32 s27, v171, 42
	v_readlane_b32 s28, v173, 42
	v_readlane_b32 s29, v175, 42
	v_mul_f32_e32 v43, s22, v43
	v_fmac_f32_e32 v177, s23, v43
	v_fmac_f32_e32 v178, s27, v43
	v_fmac_f32_e32 v179, s28, v43
	v_fmac_f32_e32 v180, s29, v43
	v_readlane_b32 s22, v167, 43
	v_readlane_b32 s23, v169, 43
	v_readlane_b32 s27, v171, 43
	v_readlane_b32 s28, v173, 43
	v_readlane_b32 s29, v175, 43
	v_mul_f32_e32 v44, s22, v44
	v_fmac_f32_e32 v177, s23, v44
	v_fmac_f32_e32 v178, s27, v44
	v_fmac_f32_e32 v179, s28, v44
	v_fmac_f32_e32 v180, s29, v44
	v_readlane_b32 s22, v167, 44
	v_readlane_b32 s23, v169, 44
	v_readlane_b32 s27, v171, 44
	v_readlane_b32 s28, v173, 44
	v_readlane_b32 s29, v175, 44
	v_mul_f32_e32 v45, s22, v45
	v_fmac_f32_e32 v177, s23, v45
	v_fmac_f32_e32 v178, s27, v45
	v_fmac_f32_e32 v179, s28, v45
	v_fmac_f32_e32 v180, s29, v45
	v_readlane_b32 s22, v167, 45
	v_readlane_b32 s23, v169, 45
	v_readlane_b32 s27, v171, 45
	v_readlane_b32 s28, v173, 45
	v_readlane_b32 s29, v175, 45
	v_mul_f32_e32 v46, s22, v46
	v_fmac_f32_e32 v177, s23, v46
	v_fmac_f32_e32 v178, s27, v46
	v_fmac_f32_e32 v179, s28, v46
	v_fmac_f32_e32 v180, s29, v46
	v_readlane_b32 s22, v167, 46
	v_readlane_b32 s23, v169, 46
	v_readlane_b32 s27, v171, 46
	v_readlane_b32 s28, v173, 46
	v_readlane_b32 s29, v175, 46
	v_mul_f32_e32 v47, s22, v47
	v_fmac_f32_e32 v177, s23, v47
	v_fmac_f32_e32 v178, s27, v47
	v_fmac_f32_e32 v179, s28, v47
	v_fmac_f32_e32 v180, s29, v47
	v_readlane_b32 s22, v167, 47
	v_readlane_b32 s23, v169, 47
	v_readlane_b32 s27, v171, 47
	v_readlane_b32 s28, v173, 47
	v_readlane_b32 s29, v175, 47
	v_mul_f32_e32 v48, s22, v48
	v_fmac_f32_e32 v177, s23, v48
	v_fmac_f32_e32 v178, s27, v48
	v_fmac_f32_e32 v179, s28, v48
	v_fmac_f32_e32 v180, s29, v48
	v_readlane_b32 s22, v167, 48
	v_readlane_b32 s23, v169, 48
	v_readlane_b32 s27, v171, 48
	v_readlane_b32 s28, v173, 48
	v_readlane_b32 s29, v175, 48
; __device__ __forceinline__ unsigned pk2(float lo, float hi) { return f2bf(lo) | (f2bf(hi) << 16); }
; __device__ __forceinline__ void phase_prep(const Args& a, LAS unsigned char* lds, int wid, int lane) {
;     ...
;           for (int o = 0; o < 128; ++o) { const float w = a.w_out_1[(size_t)(g * 128 + o) * 1024 + n] * a.pool_scale[g * 128 + o];
;               c0 += pw[o] * w; c1 += pw[128 + o] * w; c2 += pw[256 + o] * w; c3 += pw[384 + o] * w; }
;           u32x2 o2; o2.x = pk2(c0, c1); o2.y = pk2(c2, c3);
;           *(u32x2*)(WT + (size_t)n * 1024 + k) = o2; } }
	v_mul_f32_e32 v49, s22, v49
	v_fmac_f32_e32 v177, s23, v49
	v_fmac_f32_e32 v178, s27, v49
	v_fmac_f32_e32 v179, s28, v49
	v_fmac_f32_e32 v180, s29, v49
	v_readlane_b32 s22, v167, 49
	v_readlane_b32 s23, v169, 49
	v_readlane_b32 s27, v171, 49
	v_readlane_b32 s28, v173, 49
	v_readlane_b32 s29, v175, 49
	v_mul_f32_e32 v50, s22, v50
	v_fmac_f32_e32 v177, s23, v50
	v_fmac_f32_e32 v178, s27, v50
	v_fmac_f32_e32 v179, s28, v50
	v_fmac_f32_e32 v180, s29, v50
	v_readlane_b32 s22, v167, 50
	v_readlane_b32 s23, v169, 50
	v_readlane_b32 s27, v171, 50
	v_readlane_b32 s28, v173, 50
	v_readlane_b32 s29, v175, 50
	v_mul_f32_e32 v51, s22, v51
	v_fmac_f32_e32 v177, s23, v51
	v_fmac_f32_e32 v178, s27, v51
	v_fmac_f32_e32 v179, s28, v51
	v_fmac_f32_e32 v180, s29, v51
	v_readlane_b32 s22, v167, 51
	v_readlane_b32 s23, v169, 51
	v_readlane_b32 s27, v171, 51
	v_readlane_b32 s28, v173, 51
	v_readlane_b32 s29, v175, 51
	v_mul_f32_e32 v52, s22, v52
	v_fmac_f32_e32 v177, s23, v52
	v_fmac_f32_e32 v178, s27, v52
	v_fmac_f32_e32 v179, s28, v52
	v_fmac_f32_e32 v180, s29, v52
	v_readlane_b32 s22, v167, 52
	v_readlane_b32 s23, v169, 52
	v_readlane_b32 s27, v171, 52
	v_readlane_b32 s28, v173, 52
	v_readlane_b32 s29, v175, 52
	v_mul_f32_e32 v53, s22, v53
	v_fmac_f32_e32 v177, s23, v53
	v_fmac_f32_e32 v178, s27, v53
	v_fmac_f32_e32 v179, s28, v53
	v_fmac_f32_e32 v180, s29, v53
	v_readlane_b32 s22, v167, 53
	v_readlane_b32 s23, v169, 53
	v_readlane_b32 s27, v171, 53
	v_readlane_b32 s28, v173, 53
	v_readlane_b32 s29, v175, 53
	v_mul_f32_e32 v54, s22, v54
	v_fmac_f32_e32 v177, s23, v54
	v_fmac_f32_e32 v178, s27, v54
	v_fmac_f32_e32 v179, s28, v54
	v_fmac_f32_e32 v180, s29, v54
	v_readlane_b32 s22, v167, 54
	v_readlane_b32 s23, v169, 54
	v_readlane_b32 s27, v171, 54
	v_readlane_b32 s28, v173, 54
	v_readlane_b32 s29, v175, 54
	v_mul_f32_e32 v55, s22, v55
	v_fmac_f32_e32 v177, s23, v55
	v_fmac_f32_e32 v178, s27, v55
	v_fmac_f32_e32 v179, s28, v55
	v_fmac_f32_e32 v180, s29, v55
	v_readlane_b32 s22, v167, 55
	v_readlane_b32 s23, v169, 55
	v_readlane_b32 s27, v171, 55
	v_readlane_b32 s28, v173, 55
	v_readlane_b32 s29, v175, 55
	v_mul_f32_e32 v56, s22, v56
	v_fmac_f32_e32 v177, s23, v56
	v_fmac_f32_e32 v178, s27, v56
	v_fmac_f32_e32 v179, s28, v56
	v_fmac_f32_e32 v180, s29, v56
	v_readlane_b32 s22, v167, 56
	v_readlane_b32 s23, v169, 56
	v_readlane_b32 s27, v171, 56
	v_readlane_b32 s28, v173, 56
	v_readlane_b32 s29, v175, 56
	v_mul_f32_e32 v57, s22, v57
	v_fmac_f32_e32 v177, s23, v57
	v_fmac_f32_e32 v178, s27, v57
	v_fmac_f32_e32 v179, s28, v57
	v_fmac_f32_e32 v180, s29, v57
	v_readlane_b32 s22, v167, 57
	v_readlane_b32 s23, v169, 57
	v_readlane_b32 s27, v171, 57
	v_readlane_b32 s28, v173, 57
	v_readlane_b32 s29, v175, 57
	v_mul_f32_e32 v58, s22, v58
	v_fmac_f32_e32 v177, s23, v58
	v_fmac_f32_e32 v178, s27, v58
	v_fmac_f32_e32 v179, s28, v58
	v_fmac_f32_e32 v180, s29, v58
	v_readlane_b32 s22, v167, 58
	v_readlane_b32 s23, v169, 58
	v_readlane_b32 s27, v171, 58
	v_readlane_b32 s28, v173, 58
	v_readlane_b32 s29, v175, 58
	v_mul_f32_e32 v59, s22, v59
	v_fmac_f32_e32 v177, s23, v59
	v_fmac_f32_e32 v178, s27, v59
	v_fmac_f32_e32 v179, s28, v59
	v_fmac_f32_e32 v180, s29, v59
	v_readlane_b32 s22, v167, 59
	v_readlane_b32 s23, v169, 59
	v_readlane_b32 s27, v171, 59
	v_readlane_b32 s28, v173, 59
	v_readlane_b32 s29, v175, 59
	v_mul_f32_e32 v60, s22, v60
	v_fmac_f32_e32 v177, s23, v60
	v_fmac_f32_e32 v178, s27, v60
	v_fmac_f32_e32 v179, s28, v60
	v_fmac_f32_e32 v180, s29, v60
	v_readlane_b32 s22, v167, 60
	v_readlane_b32 s23, v169, 60
	v_readlane_b32 s27, v171, 60
	v_readlane_b32 s28, v173, 60
	v_readlane_b32 s29, v175, 60
	v_mul_f32_e32 v61, s22, v61
	v_fmac_f32_e32 v177, s23, v61
	v_fmac_f32_e32 v178, s27, v61
	v_fmac_f32_e32 v179, s28, v61
	v_fmac_f32_e32 v180, s29, v61
	v_readlane_b32 s22, v167, 61
	v_readlane_b32 s23, v169, 61
	v_readlane_b32 s27, v171, 61
	v_readlane_b32 s28, v173, 61
	v_readlane_b32 s29, v175, 61
	v_mul_f32_e32 v62, s22, v62
	v_fmac_f32_e32 v177, s23, v62
	v_fmac_f32_e32 v178, s27, v62
	v_fmac_f32_e32 v179, s28, v62
	v_fmac_f32_e32 v180, s29, v62
	v_readlane_b32 s22, v167, 62
	v_readlane_b32 s23, v169, 62
	v_readlane_b32 s27, v171, 62
	v_readlane_b32 s28, v173, 62
	v_readlane_b32 s29, v175, 62
	v_mul_f32_e32 v63, s22, v63
	v_fmac_f32_e32 v177, s23, v63
	v_fmac_f32_e32 v178, s27, v63
	v_fmac_f32_e32 v179, s28, v63
	v_fmac_f32_e32 v180, s29, v63
	v_readlane_b32 s22, v167, 63
	v_readlane_b32 s23, v169, 63
	v_readlane_b32 s27, v171, 63
	v_readlane_b32 s28, v173, 63
	v_readlane_b32 s29, v175, 63
	v_mul_f32_e32 v64, s22, v64
	v_fmac_f32_e32 v177, s23, v64
	v_fmac_f32_e32 v178, s27, v64
	v_fmac_f32_e32 v179, s28, v64
	v_fmac_f32_e32 v180, s29, v64
	v_cvt_pk_bf16_f32 v182, v177, v178
	v_cvt_pk_bf16_f32 v183, v179, v180
	v_lshlrev_b32_e32 v184, 11, v212
	s_lshl_b32 s6, s2, 17
	s_lshl_b32 s7, s1, 3
	s_add_u32 s6, s6, s7
	v_add_u32_e32 v184, s6, v184
	global_store_dwordx2 v184, v[182:183], s[70:71]
	s_add_u32 s17, s17, s16
	s_cmpk_lt_u32 s17, 0x800
	s_cbranch_scc1 .Lfd_loop
